# attention gate: dots for all past blocks first (kmean rows read half a block ahead), one batch of cross-half exchanges, branch-free top-3 insertion (same arithmetic order and comparisons)
# baseline (speedup 1.0000x reference)
; __device__ __forceinline__ float bf2f(unsigned v) { return __uint_as_float(v << 16); }
; __device__ void attn_item(const Params& p, char* lds, int bh, int qi) {
;     ...
;   for (int i = tid; i < 16 * 64; i += NT) km[i] = p.kmean[(size_t)bh * 16 * 64 + i];
;   const int qpos = qi * 256 + wave * 32 + l31;
;   bf16x8 qf[4];
; #pragma unroll
;   for (int ks = 0; ks < 4; ++ks) qf[ks] = *(const bf16x8*)(Qg + (size_t)qpos * 64 + ks * 16 + 8 * h);
;   __syncthreads();
;   unsigned selmask = 0;
;   if (qi <= 3) selmask = (1u << qi) - 1u;
;   else {
;     float v0 = -INFINITY, v1 = -INFINITY, v2 = -INFINITY; int i0 = 0, i1 = 0, i2 = 0;
;     for (int j = 0; j < qi; ++j) {
;       float g = 0.f;
; #pragma unroll
;       for (int ks = 0; ks < 4; ++ks) {
;         const f32x4 ka = *(const f32x4*)(km + j * 64 + ks * 16 + 8 * h);
;         const f32x4 kb = *(const f32x4*)(km + j * 64 + ks * 16 + 8 * h + 4);
; #pragma unroll
;         for (int e = 0; e < 4; ++e) {
;           g += bf2f((unsigned)(u16)qf[ks][e]) * ka[e];
;           g += bf2f((unsigned)(u16)qf[ks][4 + e]) * kb[e];
;         }
;       }
.LBB0_400:
	global_load_dword v6, v[2:3], off
	v_add_co_u32_e32 v4, vcc, 0x200, v4
	s_xor_b64 s[18:19], vcc, -1
	s_and_b64 s[18:19], exec, s[18:19]
	v_lshl_add_u64 v[2:3], v[2:3], 0, s[12:13]
	s_or_b64 s[4:5], s[18:19], s[4:5]
	s_waitcnt vmcnt(0)
	ds_write_b32 v5, v6
	v_add_u32_e32 v5, 0x800, v5
	s_andn2_b64 exec, exec, s[4:5]
	s_cbranch_execnz .LBB0_400
	s_or_b64 exec, exec, s[4:5]
	s_ashr_i32 s4, s14, 3
	s_sub_i32 s37, 15, s4
	s_lshl_b32 s6, s22, 19
	s_add_u32 s14, s8, s6
	s_addc_u32 s15, s9, 0
	s_lshl_b32 s4, s37, 8
	v_add_u32_e32 v94, s4, v113
	v_lshlrev_b64 v[2:3], 7, v[94:95]
	v_lshl_add_u64 v[2:3], s[14:15], 0, v[2:3]
	v_mov_b32_e32 v105, v95
	v_lshl_add_u64 v[2:3], v[2:3], 0, v[104:105]
	global_load_dwordx4 v[66:69], v[2:3], off
	global_load_dwordx4 v[70:73], v[2:3], off offset:32
	global_load_dwordx4 v[74:77], v[2:3], off offset:64
	global_load_dwordx4 v[78:81], v[2:3], off offset:96
	s_cmp_gt_u32 s37, 3
	s_mov_b64 s[14:15], -1
	s_waitcnt lgkmcnt(0)
	s_barrier
	s_cbranch_scc0 .LBB0_412
	v_cmp_lt_i32_e32 vcc, v156, v157
	v_mov_b32_e32 v34, 0
	s_waitcnt vmcnt(3)
	v_lshlrev_b32_e32 v15, 16, v66
	v_cndmask_b32_e32 v2, v1, v156, vcc
	v_lshlrev_b32_e32 v14, 2, v2
	v_lshlrev_b32_e32 v16, 16, v68
	v_and_b32_e32 v17, 0xffff0000, v66
	v_and_b32_e32 v18, 0xffff0000, v68
	v_lshlrev_b32_e32 v19, 16, v67
	v_lshlrev_b32_e32 v20, 16, v69
	v_and_b32_e32 v21, 0xffff0000, v67
	v_and_b32_e32 v22, 0xffff0000, v69
	s_waitcnt vmcnt(2)
	v_lshlrev_b32_e32 v23, 16, v70
	v_lshlrev_b32_e32 v24, 16, v72
	v_and_b32_e32 v25, 0xffff0000, v70
	v_and_b32_e32 v26, 0xffff0000, v72
	v_lshlrev_b32_e32 v27, 16, v71
	v_lshlrev_b32_e32 v28, 16, v73
	v_and_b32_e32 v29, 0xffff0000, v71
	v_and_b32_e32 v30, 0xffff0000, v73
	s_waitcnt vmcnt(1)
	v_lshlrev_b32_e32 v31, 16, v74
	v_lshlrev_b32_e32 v32, 16, v76
	v_and_b32_e32 v33, 0xffff0000, v74
	v_and_b32_e32 v35, 0xffff0000, v76
	v_lshlrev_b32_e32 v3, 16, v75
	v_lshlrev_b32_e32 v2, 16, v77
	v_and_b32_e32 v5, 0xffff0000, v75
	v_and_b32_e32 v4, 0xffff0000, v77
	s_waitcnt vmcnt(0)
	v_lshlrev_b32_e32 v7, 16, v78
	v_lshlrev_b32_e32 v6, 16, v80
	v_and_b32_e32 v9, 0xffff0000, v78
	v_and_b32_e32 v8, 0xffff0000, v80
	v_lshlrev_b32_e32 v11, 16, v79
	v_lshlrev_b32_e32 v10, 16, v81
	v_and_b32_e32 v13, 0xffff0000, v79
	v_and_b32_e32 v12, 0xffff0000, v81
	v_mov_b32_e32 v37, 0xff800000
	s_mov_b32 s5, 0
	v_mov_b32_e32 v36, v123
	v_mov_b32_e32 v38, 0xff800000
	v_mov_b32_e32 v41, 0xff800000
	v_mov_b32_e32 v39, 0
	v_mov_b32_e32 v40, 0
	ds_read_b128 v[42:45], v36
	ds_read_b128 v[46:49], v36 offset:16
	ds_read_b128 v[50:53], v36 offset:64
	ds_read_b128 v[54:57], v36 offset:80
	ds_read_b128 v[176:179], v36 offset:128
	ds_read_b128 v[180:183], v36 offset:144
	ds_read_b128 v[184:187], v36 offset:192
	ds_read_b128 v[188:191], v36 offset:208
	s_waitcnt lgkmcnt(7)
	s_waitcnt lgkmcnt(6)
	v_fma_f32 v61, v42, v15, 0
	v_fmac_f32_e32 v61, v46, v16
	v_fmac_f32_e32 v61, v43, v17
	v_fmac_f32_e32 v61, v47, v18
	v_fmac_f32_e32 v61, v44, v19
	v_fmac_f32_e32 v61, v48, v20
	v_fmac_f32_e32 v61, v45, v21
	v_fmac_f32_e32 v61, v49, v22
	s_waitcnt lgkmcnt(5)
	s_waitcnt lgkmcnt(4)
	v_fmac_f32_e32 v61, v50, v23
	v_fmac_f32_e32 v61, v54, v24
	v_fmac_f32_e32 v61, v51, v25
	v_fmac_f32_e32 v61, v55, v26
	v_fmac_f32_e32 v61, v52, v27
	v_fmac_f32_e32 v61, v56, v28
	v_fmac_f32_e32 v61, v53, v29
	v_fmac_f32_e32 v61, v57, v30
	ds_read_b128 v[42:45], v36 offset:256
	ds_read_b128 v[46:49], v36 offset:272
	ds_read_b128 v[50:53], v36 offset:320
	ds_read_b128 v[54:57], v36 offset:336
	s_waitcnt lgkmcnt(7)
	s_waitcnt lgkmcnt(6)
	v_fmac_f32_e32 v61, v176, v31
	v_fmac_f32_e32 v61, v180, v32
	v_fmac_f32_e32 v61, v177, v33
	v_fmac_f32_e32 v61, v181, v35
	v_mul_f32_e32 v62, v178, v3
	v_add_f32_e32 v61, v62, v61
	v_mul_f32_e32 v62, v182, v2
	v_add_f32_e32 v61, v62, v61
	v_mul_f32_e32 v62, v179, v5
	v_add_f32_e32 v61, v62, v61
	v_mul_f32_e32 v62, v183, v4
	v_add_f32_e32 v61, v62, v61
	s_waitcnt lgkmcnt(5)
	s_waitcnt lgkmcnt(4)
	v_mul_f32_e32 v62, v184, v7
	v_add_f32_e32 v61, v62, v61
	v_mul_f32_e32 v62, v188, v6
	v_add_f32_e32 v61, v62, v61
	v_mul_f32_e32 v62, v185, v9
	v_add_f32_e32 v61, v62, v61
	v_mul_f32_e32 v62, v189, v8
	v_add_f32_e32 v61, v62, v61
	v_mul_f32_e32 v62, v186, v11
	v_add_f32_e32 v61, v62, v61
	v_mul_f32_e32 v62, v190, v10
	v_add_f32_e32 v61, v62, v61
	v_mul_f32_e32 v62, v187, v13
	v_add_f32_e32 v61, v62, v61
	v_mul_f32_e32 v62, v191, v12
	v_add_f32_e32 v61, v62, v61
	v_mov_b32_e32 v193, v61
	ds_read_b128 v[176:179], v36 offset:384
	ds_read_b128 v[180:183], v36 offset:400
	ds_read_b128 v[184:187], v36 offset:448
	ds_read_b128 v[188:191], v36 offset:464
	s_waitcnt lgkmcnt(7)
	s_waitcnt lgkmcnt(6)
	v_fma_f32 v61, v42, v15, 0
	v_fmac_f32_e32 v61, v46, v16
	v_fmac_f32_e32 v61, v43, v17
	v_fmac_f32_e32 v61, v47, v18
	v_fmac_f32_e32 v61, v44, v19
	v_fmac_f32_e32 v61, v48, v20
	v_fmac_f32_e32 v61, v45, v21
	v_fmac_f32_e32 v61, v49, v22
	s_waitcnt lgkmcnt(5)
	s_waitcnt lgkmcnt(4)
	v_fmac_f32_e32 v61, v50, v23
	v_fmac_f32_e32 v61, v54, v24
	v_fmac_f32_e32 v61, v51, v25
	v_fmac_f32_e32 v61, v55, v26
	v_fmac_f32_e32 v61, v52, v27
	v_fmac_f32_e32 v61, v56, v28
	v_fmac_f32_e32 v61, v53, v29
	v_fmac_f32_e32 v61, v57, v30
	ds_read_b128 v[42:45], v36 offset:512
	ds_read_b128 v[46:49], v36 offset:528
	ds_read_b128 v[50:53], v36 offset:576
	ds_read_b128 v[54:57], v36 offset:592
	s_waitcnt lgkmcnt(7)
	s_waitcnt lgkmcnt(6)
	v_fmac_f32_e32 v61, v176, v31
	v_fmac_f32_e32 v61, v180, v32
	v_fmac_f32_e32 v61, v177, v33
	v_fmac_f32_e32 v61, v181, v35
	v_mul_f32_e32 v62, v178, v3
	v_add_f32_e32 v61, v62, v61
	v_mul_f32_e32 v62, v182, v2
	v_add_f32_e32 v61, v62, v61
	v_mul_f32_e32 v62, v179, v5
	v_add_f32_e32 v61, v62, v61
	v_mul_f32_e32 v62, v183, v4
	v_add_f32_e32 v61, v62, v61
	s_waitcnt lgkmcnt(5)
; __device__ __forceinline__ float bf2f(unsigned v) { return __uint_as_float(v << 16); }
; __device__ void attn_item(const Params& p, char* lds, int bh, int qi) {
;     ...
;     for (int j = 0; j < qi; ++j) {
;       float g = 0.f;
; #pragma unroll
;       for (int ks = 0; ks < 4; ++ks) {
;         const f32x4 ka = *(const f32x4*)(km + j * 64 + ks * 16 + 8 * h);
;         const f32x4 kb = *(const f32x4*)(km + j * 64 + ks * 16 + 8 * h + 4);
; #pragma unroll
;         for (int e = 0; e < 4; ++e) {
;           g += bf2f((unsigned)(u16)qf[ks][e]) * ka[e];
;           g += bf2f((unsigned)(u16)qf[ks][4 + e]) * kb[e];
;         }
;       }
	s_waitcnt lgkmcnt(4)
	v_mul_f32_e32 v62, v184, v7
	v_add_f32_e32 v61, v62, v61
	v_mul_f32_e32 v62, v188, v6
	v_add_f32_e32 v61, v62, v61
	v_mul_f32_e32 v62, v185, v9
	v_add_f32_e32 v61, v62, v61
	v_mul_f32_e32 v62, v189, v8
	v_add_f32_e32 v61, v62, v61
	v_mul_f32_e32 v62, v186, v11
	v_add_f32_e32 v61, v62, v61
	v_mul_f32_e32 v62, v190, v10
	v_add_f32_e32 v61, v62, v61
	v_mul_f32_e32 v62, v187, v13
	v_add_f32_e32 v61, v62, v61
	v_mul_f32_e32 v62, v191, v12
	v_add_f32_e32 v61, v62, v61
	v_mov_b32_e32 v194, v61
	ds_read_b128 v[176:179], v36 offset:640
	ds_read_b128 v[180:183], v36 offset:656
	ds_read_b128 v[184:187], v36 offset:704
	ds_read_b128 v[188:191], v36 offset:720
	s_waitcnt lgkmcnt(7)
	s_waitcnt lgkmcnt(6)
	v_fma_f32 v61, v42, v15, 0
	v_fmac_f32_e32 v61, v46, v16
	v_fmac_f32_e32 v61, v43, v17
	v_fmac_f32_e32 v61, v47, v18
	v_fmac_f32_e32 v61, v44, v19
	v_fmac_f32_e32 v61, v48, v20
	v_fmac_f32_e32 v61, v45, v21
	v_fmac_f32_e32 v61, v49, v22
	s_waitcnt lgkmcnt(5)
	s_waitcnt lgkmcnt(4)
	v_fmac_f32_e32 v61, v50, v23
	v_fmac_f32_e32 v61, v54, v24
	v_fmac_f32_e32 v61, v51, v25
	v_fmac_f32_e32 v61, v55, v26
	v_fmac_f32_e32 v61, v52, v27
	v_fmac_f32_e32 v61, v56, v28
	v_fmac_f32_e32 v61, v53, v29
	v_fmac_f32_e32 v61, v57, v30
	ds_read_b128 v[42:45], v36 offset:768
	ds_read_b128 v[46:49], v36 offset:784
	ds_read_b128 v[50:53], v36 offset:832
	ds_read_b128 v[54:57], v36 offset:848
	s_waitcnt lgkmcnt(7)
	s_waitcnt lgkmcnt(6)
	v_fmac_f32_e32 v61, v176, v31
	v_fmac_f32_e32 v61, v180, v32
	v_fmac_f32_e32 v61, v177, v33
	v_fmac_f32_e32 v61, v181, v35
	v_mul_f32_e32 v62, v178, v3
	v_add_f32_e32 v61, v62, v61
	v_mul_f32_e32 v62, v182, v2
	v_add_f32_e32 v61, v62, v61
	v_mul_f32_e32 v62, v179, v5
	v_add_f32_e32 v61, v62, v61
	v_mul_f32_e32 v62, v183, v4
	v_add_f32_e32 v61, v62, v61
	s_waitcnt lgkmcnt(5)
	s_waitcnt lgkmcnt(4)
	v_mul_f32_e32 v62, v184, v7
	v_add_f32_e32 v61, v62, v61
	v_mul_f32_e32 v62, v188, v6
	v_add_f32_e32 v61, v62, v61
	v_mul_f32_e32 v62, v185, v9
	v_add_f32_e32 v61, v62, v61
	v_mul_f32_e32 v62, v189, v8
	v_add_f32_e32 v61, v62, v61
	v_mul_f32_e32 v62, v186, v11
	v_add_f32_e32 v61, v62, v61
	v_mul_f32_e32 v62, v190, v10
	v_add_f32_e32 v61, v62, v61
	v_mul_f32_e32 v62, v187, v13
	v_add_f32_e32 v61, v62, v61
	v_mul_f32_e32 v62, v191, v12
	v_add_f32_e32 v61, v62, v61
	v_mov_b32_e32 v195, v61
	ds_read_b128 v[176:179], v36 offset:896
	ds_read_b128 v[180:183], v36 offset:912
	ds_read_b128 v[184:187], v36 offset:960
	ds_read_b128 v[188:191], v36 offset:976
	s_waitcnt lgkmcnt(7)
	s_waitcnt lgkmcnt(6)
	v_fma_f32 v61, v42, v15, 0
	v_fmac_f32_e32 v61, v46, v16
	v_fmac_f32_e32 v61, v43, v17
	v_fmac_f32_e32 v61, v47, v18
	v_fmac_f32_e32 v61, v44, v19
	v_fmac_f32_e32 v61, v48, v20
	v_fmac_f32_e32 v61, v45, v21
	v_fmac_f32_e32 v61, v49, v22
	s_waitcnt lgkmcnt(5)
	s_waitcnt lgkmcnt(4)
	v_fmac_f32_e32 v61, v50, v23
	v_fmac_f32_e32 v61, v54, v24
	v_fmac_f32_e32 v61, v51, v25
	v_fmac_f32_e32 v61, v55, v26
	v_fmac_f32_e32 v61, v52, v27
	v_fmac_f32_e32 v61, v56, v28
	v_fmac_f32_e32 v61, v53, v29
	v_fmac_f32_e32 v61, v57, v30
	ds_read_b128 v[42:45], v36 offset:1024
	ds_read_b128 v[46:49], v36 offset:1040
	ds_read_b128 v[50:53], v36 offset:1088
	ds_read_b128 v[54:57], v36 offset:1104
	s_waitcnt lgkmcnt(7)
	s_waitcnt lgkmcnt(6)
	v_fmac_f32_e32 v61, v176, v31
	v_fmac_f32_e32 v61, v180, v32
	v_fmac_f32_e32 v61, v177, v33
	v_fmac_f32_e32 v61, v181, v35
	v_mul_f32_e32 v62, v178, v3
	v_add_f32_e32 v61, v62, v61
	v_mul_f32_e32 v62, v182, v2
	v_add_f32_e32 v61, v62, v61
	v_mul_f32_e32 v62, v179, v5
	v_add_f32_e32 v61, v62, v61
	v_mul_f32_e32 v62, v183, v4
	v_add_f32_e32 v61, v62, v61
	s_waitcnt lgkmcnt(5)
	s_waitcnt lgkmcnt(4)
	v_mul_f32_e32 v62, v184, v7
	v_add_f32_e32 v61, v62, v61
	v_mul_f32_e32 v62, v188, v6
	v_add_f32_e32 v61, v62, v61
	v_mul_f32_e32 v62, v185, v9
	v_add_f32_e32 v61, v62, v61
	v_mul_f32_e32 v62, v189, v8
	v_add_f32_e32 v61, v62, v61
	v_mul_f32_e32 v62, v186, v11
	v_add_f32_e32 v61, v62, v61
	v_mul_f32_e32 v62, v190, v10
	v_add_f32_e32 v61, v62, v61
	v_mul_f32_e32 v62, v187, v13
	v_add_f32_e32 v61, v62, v61
	v_mul_f32_e32 v62, v191, v12
	v_add_f32_e32 v61, v62, v61
	v_mov_b32_e32 v196, v61
	ds_read_b128 v[176:179], v36 offset:1152
	ds_read_b128 v[180:183], v36 offset:1168
	ds_read_b128 v[184:187], v36 offset:1216
	ds_read_b128 v[188:191], v36 offset:1232
	s_cmp_eq_u32 s37, 4
	s_cbranch_scc1 .Lgate_b
	s_waitcnt lgkmcnt(7)
	s_waitcnt lgkmcnt(6)
	v_fma_f32 v61, v42, v15, 0
	v_fmac_f32_e32 v61, v46, v16
	v_fmac_f32_e32 v61, v43, v17
	v_fmac_f32_e32 v61, v47, v18
	v_fmac_f32_e32 v61, v44, v19
	v_fmac_f32_e32 v61, v48, v20
	v_fmac_f32_e32 v61, v45, v21
	v_fmac_f32_e32 v61, v49, v22
	s_waitcnt lgkmcnt(5)
	s_waitcnt lgkmcnt(4)
	v_fmac_f32_e32 v61, v50, v23
	v_fmac_f32_e32 v61, v54, v24
	v_fmac_f32_e32 v61, v51, v25
	v_fmac_f32_e32 v61, v55, v26
	v_fmac_f32_e32 v61, v52, v27
	v_fmac_f32_e32 v61, v56, v28
	v_fmac_f32_e32 v61, v53, v29
	v_fmac_f32_e32 v61, v57, v30
	ds_read_b128 v[42:45], v36 offset:1280
	ds_read_b128 v[46:49], v36 offset:1296
	ds_read_b128 v[50:53], v36 offset:1344
	ds_read_b128 v[54:57], v36 offset:1360
	s_waitcnt lgkmcnt(7)
	s_waitcnt lgkmcnt(6)
	v_fmac_f32_e32 v61, v176, v31
	v_fmac_f32_e32 v61, v180, v32
	v_fmac_f32_e32 v61, v177, v33
	v_fmac_f32_e32 v61, v181, v35
	v_mul_f32_e32 v62, v178, v3
	v_add_f32_e32 v61, v62, v61
	v_mul_f32_e32 v62, v182, v2
	v_add_f32_e32 v61, v62, v61
	v_mul_f32_e32 v62, v179, v5
	v_add_f32_e32 v61, v62, v61
	v_mul_f32_e32 v62, v183, v4
	v_add_f32_e32 v61, v62, v61
	s_waitcnt lgkmcnt(5)
	s_waitcnt lgkmcnt(4)
	v_mul_f32_e32 v62, v184, v7
	v_add_f32_e32 v61, v62, v61
	v_mul_f32_e32 v62, v188, v6
	v_add_f32_e32 v61, v62, v61
	v_mul_f32_e32 v62, v185, v9
	v_add_f32_e32 v61, v62, v61
	v_mul_f32_e32 v62, v189, v8
	v_add_f32_e32 v61, v62, v61
	v_mul_f32_e32 v62, v186, v11
	v_add_f32_e32 v61, v62, v61
	v_mul_f32_e32 v62, v190, v10
	v_add_f32_e32 v61, v62, v61
	v_mul_f32_e32 v62, v187, v13
	v_add_f32_e32 v61, v62, v61
	v_mul_f32_e32 v62, v191, v12
	v_add_f32_e32 v61, v62, v61
	v_mov_b32_e32 v197, v61
	ds_read_b128 v[176:179], v36 offset:1408
	ds_read_b128 v[180:183], v36 offset:1424
	ds_read_b128 v[184:187], v36 offset:1472
	ds_read_b128 v[188:191], v36 offset:1488
	s_cmp_eq_u32 s37, 5
	s_cbranch_scc1 .Lgate_b
; __device__ __forceinline__ float bf2f(unsigned v) { return __uint_as_float(v << 16); }
; __device__ void attn_item(const Params& p, char* lds, int bh, int qi) {
;     ...
;     for (int j = 0; j < qi; ++j) {
;       float g = 0.f;
; #pragma unroll
;       for (int ks = 0; ks < 4; ++ks) {
;         const f32x4 ka = *(const f32x4*)(km + j * 64 + ks * 16 + 8 * h);
;         const f32x4 kb = *(const f32x4*)(km + j * 64 + ks * 16 + 8 * h + 4);
; #pragma unroll
;         for (int e = 0; e < 4; ++e) {
;           g += bf2f((unsigned)(u16)qf[ks][e]) * ka[e];
;           g += bf2f((unsigned)(u16)qf[ks][4 + e]) * kb[e];
;         }
;       }
	s_waitcnt lgkmcnt(7)
	s_waitcnt lgkmcnt(6)
	v_fma_f32 v61, v42, v15, 0
	v_fmac_f32_e32 v61, v46, v16
	v_fmac_f32_e32 v61, v43, v17
	v_fmac_f32_e32 v61, v47, v18
	v_fmac_f32_e32 v61, v44, v19
	v_fmac_f32_e32 v61, v48, v20
	v_fmac_f32_e32 v61, v45, v21
	v_fmac_f32_e32 v61, v49, v22
	s_waitcnt lgkmcnt(5)
	s_waitcnt lgkmcnt(4)
	v_fmac_f32_e32 v61, v50, v23
	v_fmac_f32_e32 v61, v54, v24
	v_fmac_f32_e32 v61, v51, v25
	v_fmac_f32_e32 v61, v55, v26
	v_fmac_f32_e32 v61, v52, v27
	v_fmac_f32_e32 v61, v56, v28
	v_fmac_f32_e32 v61, v53, v29
	v_fmac_f32_e32 v61, v57, v30
	ds_read_b128 v[42:45], v36 offset:1536
	ds_read_b128 v[46:49], v36 offset:1552
	ds_read_b128 v[50:53], v36 offset:1600
	ds_read_b128 v[54:57], v36 offset:1616
	s_waitcnt lgkmcnt(7)
	s_waitcnt lgkmcnt(6)
	v_fmac_f32_e32 v61, v176, v31
	v_fmac_f32_e32 v61, v180, v32
	v_fmac_f32_e32 v61, v177, v33
	v_fmac_f32_e32 v61, v181, v35
	v_mul_f32_e32 v62, v178, v3
	v_add_f32_e32 v61, v62, v61
	v_mul_f32_e32 v62, v182, v2
	v_add_f32_e32 v61, v62, v61
	v_mul_f32_e32 v62, v179, v5
	v_add_f32_e32 v61, v62, v61
	v_mul_f32_e32 v62, v183, v4
	v_add_f32_e32 v61, v62, v61
	s_waitcnt lgkmcnt(5)
	s_waitcnt lgkmcnt(4)
	v_mul_f32_e32 v62, v184, v7
	v_add_f32_e32 v61, v62, v61
	v_mul_f32_e32 v62, v188, v6
	v_add_f32_e32 v61, v62, v61
	v_mul_f32_e32 v62, v185, v9
	v_add_f32_e32 v61, v62, v61
	v_mul_f32_e32 v62, v189, v8
	v_add_f32_e32 v61, v62, v61
	v_mul_f32_e32 v62, v186, v11
	v_add_f32_e32 v61, v62, v61
	v_mul_f32_e32 v62, v190, v10
	v_add_f32_e32 v61, v62, v61
	v_mul_f32_e32 v62, v187, v13
	v_add_f32_e32 v61, v62, v61
	v_mul_f32_e32 v62, v191, v12
	v_add_f32_e32 v61, v62, v61
	v_mov_b32_e32 v198, v61
	ds_read_b128 v[176:179], v36 offset:1664
	ds_read_b128 v[180:183], v36 offset:1680
	ds_read_b128 v[184:187], v36 offset:1728
	ds_read_b128 v[188:191], v36 offset:1744
	s_cmp_eq_u32 s37, 6
	s_cbranch_scc1 .Lgate_b
	s_waitcnt lgkmcnt(7)
	s_waitcnt lgkmcnt(6)
	v_fma_f32 v61, v42, v15, 0
	v_fmac_f32_e32 v61, v46, v16
	v_fmac_f32_e32 v61, v43, v17
	v_fmac_f32_e32 v61, v47, v18
	v_fmac_f32_e32 v61, v44, v19
	v_fmac_f32_e32 v61, v48, v20
	v_fmac_f32_e32 v61, v45, v21
	v_fmac_f32_e32 v61, v49, v22
	s_waitcnt lgkmcnt(5)
	s_waitcnt lgkmcnt(4)
	v_fmac_f32_e32 v61, v50, v23
	v_fmac_f32_e32 v61, v54, v24
	v_fmac_f32_e32 v61, v51, v25
	v_fmac_f32_e32 v61, v55, v26
	v_fmac_f32_e32 v61, v52, v27
	v_fmac_f32_e32 v61, v56, v28
	v_fmac_f32_e32 v61, v53, v29
	v_fmac_f32_e32 v61, v57, v30
	ds_read_b128 v[42:45], v36 offset:1792
	ds_read_b128 v[46:49], v36 offset:1808
	ds_read_b128 v[50:53], v36 offset:1856
	ds_read_b128 v[54:57], v36 offset:1872
	s_waitcnt lgkmcnt(7)
	s_waitcnt lgkmcnt(6)
	v_fmac_f32_e32 v61, v176, v31
	v_fmac_f32_e32 v61, v180, v32
	v_fmac_f32_e32 v61, v177, v33
	v_fmac_f32_e32 v61, v181, v35
	v_mul_f32_e32 v62, v178, v3
	v_add_f32_e32 v61, v62, v61
	v_mul_f32_e32 v62, v182, v2
	v_add_f32_e32 v61, v62, v61
	v_mul_f32_e32 v62, v179, v5
	v_add_f32_e32 v61, v62, v61
	v_mul_f32_e32 v62, v183, v4
	v_add_f32_e32 v61, v62, v61
	s_waitcnt lgkmcnt(5)
	s_waitcnt lgkmcnt(4)
	v_mul_f32_e32 v62, v184, v7
	v_add_f32_e32 v61, v62, v61
	v_mul_f32_e32 v62, v188, v6
	v_add_f32_e32 v61, v62, v61
	v_mul_f32_e32 v62, v185, v9
	v_add_f32_e32 v61, v62, v61
	v_mul_f32_e32 v62, v189, v8
	v_add_f32_e32 v61, v62, v61
	v_mul_f32_e32 v62, v186, v11
	v_add_f32_e32 v61, v62, v61
	v_mul_f32_e32 v62, v190, v10
	v_add_f32_e32 v61, v62, v61
	v_mul_f32_e32 v62, v187, v13
	v_add_f32_e32 v61, v62, v61
	v_mul_f32_e32 v62, v191, v12
	v_add_f32_e32 v61, v62, v61
	v_mov_b32_e32 v199, v61
	ds_read_b128 v[176:179], v36 offset:1920
	ds_read_b128 v[180:183], v36 offset:1936
	ds_read_b128 v[184:187], v36 offset:1984
	ds_read_b128 v[188:191], v36 offset:2000
	s_cmp_eq_u32 s37, 7
	s_cbranch_scc1 .Lgate_b
	s_waitcnt lgkmcnt(7)
	s_waitcnt lgkmcnt(6)
	v_fma_f32 v61, v42, v15, 0
	v_fmac_f32_e32 v61, v46, v16
	v_fmac_f32_e32 v61, v43, v17
	v_fmac_f32_e32 v61, v47, v18
	v_fmac_f32_e32 v61, v44, v19
	v_fmac_f32_e32 v61, v48, v20
	v_fmac_f32_e32 v61, v45, v21
	v_fmac_f32_e32 v61, v49, v22
	s_waitcnt lgkmcnt(5)
	s_waitcnt lgkmcnt(4)
	v_fmac_f32_e32 v61, v50, v23
	v_fmac_f32_e32 v61, v54, v24
	v_fmac_f32_e32 v61, v51, v25
	v_fmac_f32_e32 v61, v55, v26
	v_fmac_f32_e32 v61, v52, v27
	v_fmac_f32_e32 v61, v56, v28
	v_fmac_f32_e32 v61, v53, v29
	v_fmac_f32_e32 v61, v57, v30
	ds_read_b128 v[42:45], v36 offset:2048
	ds_read_b128 v[46:49], v36 offset:2064
	ds_read_b128 v[50:53], v36 offset:2112
	ds_read_b128 v[54:57], v36 offset:2128
	s_waitcnt lgkmcnt(7)
	s_waitcnt lgkmcnt(6)
	v_fmac_f32_e32 v61, v176, v31
	v_fmac_f32_e32 v61, v180, v32
	v_fmac_f32_e32 v61, v177, v33
	v_fmac_f32_e32 v61, v181, v35
	v_mul_f32_e32 v62, v178, v3
	v_add_f32_e32 v61, v62, v61
	v_mul_f32_e32 v62, v182, v2
	v_add_f32_e32 v61, v62, v61
	v_mul_f32_e32 v62, v179, v5
	v_add_f32_e32 v61, v62, v61
	v_mul_f32_e32 v62, v183, v4
	v_add_f32_e32 v61, v62, v61
	s_waitcnt lgkmcnt(5)
	s_waitcnt lgkmcnt(4)
	v_mul_f32_e32 v62, v184, v7
	v_add_f32_e32 v61, v62, v61
	v_mul_f32_e32 v62, v188, v6
	v_add_f32_e32 v61, v62, v61
	v_mul_f32_e32 v62, v185, v9
	v_add_f32_e32 v61, v62, v61
	v_mul_f32_e32 v62, v189, v8
	v_add_f32_e32 v61, v62, v61
	v_mul_f32_e32 v62, v186, v11
	v_add_f32_e32 v61, v62, v61
	v_mul_f32_e32 v62, v190, v10
	v_add_f32_e32 v61, v62, v61
	v_mul_f32_e32 v62, v187, v13
	v_add_f32_e32 v61, v62, v61
	v_mul_f32_e32 v62, v191, v12
	v_add_f32_e32 v61, v62, v61
	v_mov_b32_e32 v200, v61
	ds_read_b128 v[176:179], v36 offset:2176
	ds_read_b128 v[180:183], v36 offset:2192
	ds_read_b128 v[184:187], v36 offset:2240
	ds_read_b128 v[188:191], v36 offset:2256
	s_cmp_eq_u32 s37, 8
	s_cbranch_scc1 .Lgate_b
; __device__ __forceinline__ float bf2f(unsigned v) { return __uint_as_float(v << 16); }
; __device__ void attn_item(const Params& p, char* lds, int bh, int qi) {
;     ...
;     for (int j = 0; j < qi; ++j) {
;       float g = 0.f;
; #pragma unroll
;       for (int ks = 0; ks < 4; ++ks) {
;         const f32x4 ka = *(const f32x4*)(km + j * 64 + ks * 16 + 8 * h);
;         const f32x4 kb = *(const f32x4*)(km + j * 64 + ks * 16 + 8 * h + 4);
; #pragma unroll
;         for (int e = 0; e < 4; ++e) {
;           g += bf2f((unsigned)(u16)qf[ks][e]) * ka[e];
;           g += bf2f((unsigned)(u16)qf[ks][4 + e]) * kb[e];
;         }
;       }
	s_waitcnt lgkmcnt(7)
	s_waitcnt lgkmcnt(6)
	v_fma_f32 v61, v42, v15, 0
	v_fmac_f32_e32 v61, v46, v16
	v_fmac_f32_e32 v61, v43, v17
	v_fmac_f32_e32 v61, v47, v18
	v_fmac_f32_e32 v61, v44, v19
	v_fmac_f32_e32 v61, v48, v20
	v_fmac_f32_e32 v61, v45, v21
	v_fmac_f32_e32 v61, v49, v22
	s_waitcnt lgkmcnt(5)
	s_waitcnt lgkmcnt(4)
	v_fmac_f32_e32 v61, v50, v23
	v_fmac_f32_e32 v61, v54, v24
	v_fmac_f32_e32 v61, v51, v25
	v_fmac_f32_e32 v61, v55, v26
	v_fmac_f32_e32 v61, v52, v27
	v_fmac_f32_e32 v61, v56, v28
	v_fmac_f32_e32 v61, v53, v29
	v_fmac_f32_e32 v61, v57, v30
	ds_read_b128 v[42:45], v36 offset:2304
	ds_read_b128 v[46:49], v36 offset:2320
	ds_read_b128 v[50:53], v36 offset:2368
	ds_read_b128 v[54:57], v36 offset:2384
	s_waitcnt lgkmcnt(7)
	s_waitcnt lgkmcnt(6)
	v_fmac_f32_e32 v61, v176, v31
	v_fmac_f32_e32 v61, v180, v32
	v_fmac_f32_e32 v61, v177, v33
	v_fmac_f32_e32 v61, v181, v35
	v_mul_f32_e32 v62, v178, v3
	v_add_f32_e32 v61, v62, v61
	v_mul_f32_e32 v62, v182, v2
	v_add_f32_e32 v61, v62, v61
	v_mul_f32_e32 v62, v179, v5
	v_add_f32_e32 v61, v62, v61
	v_mul_f32_e32 v62, v183, v4
	v_add_f32_e32 v61, v62, v61
	s_waitcnt lgkmcnt(5)
	s_waitcnt lgkmcnt(4)
	v_mul_f32_e32 v62, v184, v7
	v_add_f32_e32 v61, v62, v61
	v_mul_f32_e32 v62, v188, v6
	v_add_f32_e32 v61, v62, v61
	v_mul_f32_e32 v62, v185, v9
	v_add_f32_e32 v61, v62, v61
	v_mul_f32_e32 v62, v189, v8
	v_add_f32_e32 v61, v62, v61
	v_mul_f32_e32 v62, v186, v11
	v_add_f32_e32 v61, v62, v61
	v_mul_f32_e32 v62, v190, v10
	v_add_f32_e32 v61, v62, v61
	v_mul_f32_e32 v62, v187, v13
	v_add_f32_e32 v61, v62, v61
	v_mul_f32_e32 v62, v191, v12
	v_add_f32_e32 v61, v62, v61
	v_mov_b32_e32 v201, v61
	ds_read_b128 v[176:179], v36 offset:2432
	ds_read_b128 v[180:183], v36 offset:2448
	ds_read_b128 v[184:187], v36 offset:2496
	ds_read_b128 v[188:191], v36 offset:2512
	s_cmp_eq_u32 s37, 9
	s_cbranch_scc1 .Lgate_b
	s_waitcnt lgkmcnt(7)
	s_waitcnt lgkmcnt(6)
	v_fma_f32 v61, v42, v15, 0
	v_fmac_f32_e32 v61, v46, v16
	v_fmac_f32_e32 v61, v43, v17
	v_fmac_f32_e32 v61, v47, v18
	v_fmac_f32_e32 v61, v44, v19
	v_fmac_f32_e32 v61, v48, v20
	v_fmac_f32_e32 v61, v45, v21
	v_fmac_f32_e32 v61, v49, v22
	s_waitcnt lgkmcnt(5)
	s_waitcnt lgkmcnt(4)
	v_fmac_f32_e32 v61, v50, v23
	v_fmac_f32_e32 v61, v54, v24
	v_fmac_f32_e32 v61, v51, v25
	v_fmac_f32_e32 v61, v55, v26
	v_fmac_f32_e32 v61, v52, v27
	v_fmac_f32_e32 v61, v56, v28
	v_fmac_f32_e32 v61, v53, v29
	v_fmac_f32_e32 v61, v57, v30
	ds_read_b128 v[42:45], v36 offset:2560
	ds_read_b128 v[46:49], v36 offset:2576
	ds_read_b128 v[50:53], v36 offset:2624
	ds_read_b128 v[54:57], v36 offset:2640
	s_waitcnt lgkmcnt(7)
	s_waitcnt lgkmcnt(6)
	v_fmac_f32_e32 v61, v176, v31
	v_fmac_f32_e32 v61, v180, v32
	v_fmac_f32_e32 v61, v177, v33
	v_fmac_f32_e32 v61, v181, v35
	v_mul_f32_e32 v62, v178, v3
	v_add_f32_e32 v61, v62, v61
	v_mul_f32_e32 v62, v182, v2
	v_add_f32_e32 v61, v62, v61
	v_mul_f32_e32 v62, v179, v5
	v_add_f32_e32 v61, v62, v61
	v_mul_f32_e32 v62, v183, v4
	v_add_f32_e32 v61, v62, v61
	s_waitcnt lgkmcnt(5)
	s_waitcnt lgkmcnt(4)
	v_mul_f32_e32 v62, v184, v7
	v_add_f32_e32 v61, v62, v61
	v_mul_f32_e32 v62, v188, v6
	v_add_f32_e32 v61, v62, v61
	v_mul_f32_e32 v62, v185, v9
	v_add_f32_e32 v61, v62, v61
	v_mul_f32_e32 v62, v189, v8
	v_add_f32_e32 v61, v62, v61
	v_mul_f32_e32 v62, v186, v11
	v_add_f32_e32 v61, v62, v61
	v_mul_f32_e32 v62, v190, v10
	v_add_f32_e32 v61, v62, v61
	v_mul_f32_e32 v62, v187, v13
	v_add_f32_e32 v61, v62, v61
	v_mul_f32_e32 v62, v191, v12
	v_add_f32_e32 v61, v62, v61
	v_mov_b32_e32 v202, v61
	ds_read_b128 v[176:179], v36 offset:2688
	ds_read_b128 v[180:183], v36 offset:2704
	ds_read_b128 v[184:187], v36 offset:2752
	ds_read_b128 v[188:191], v36 offset:2768
	s_cmp_eq_u32 s37, 10
	s_cbranch_scc1 .Lgate_b
	s_waitcnt lgkmcnt(7)
	s_waitcnt lgkmcnt(6)
	v_fma_f32 v61, v42, v15, 0
	v_fmac_f32_e32 v61, v46, v16
	v_fmac_f32_e32 v61, v43, v17
	v_fmac_f32_e32 v61, v47, v18
	v_fmac_f32_e32 v61, v44, v19
	v_fmac_f32_e32 v61, v48, v20
	v_fmac_f32_e32 v61, v45, v21
	v_fmac_f32_e32 v61, v49, v22
	s_waitcnt lgkmcnt(5)
	s_waitcnt lgkmcnt(4)
	v_fmac_f32_e32 v61, v50, v23
	v_fmac_f32_e32 v61, v54, v24
	v_fmac_f32_e32 v61, v51, v25
	v_fmac_f32_e32 v61, v55, v26
	v_fmac_f32_e32 v61, v52, v27
	v_fmac_f32_e32 v61, v56, v28
	v_fmac_f32_e32 v61, v53, v29
	v_fmac_f32_e32 v61, v57, v30
	ds_read_b128 v[42:45], v36 offset:2816
	ds_read_b128 v[46:49], v36 offset:2832
	ds_read_b128 v[50:53], v36 offset:2880
	ds_read_b128 v[54:57], v36 offset:2896
	s_waitcnt lgkmcnt(7)
	s_waitcnt lgkmcnt(6)
	v_fmac_f32_e32 v61, v176, v31
	v_fmac_f32_e32 v61, v180, v32
	v_fmac_f32_e32 v61, v177, v33
	v_fmac_f32_e32 v61, v181, v35
	v_mul_f32_e32 v62, v178, v3
	v_add_f32_e32 v61, v62, v61
	v_mul_f32_e32 v62, v182, v2
	v_add_f32_e32 v61, v62, v61
	v_mul_f32_e32 v62, v179, v5
	v_add_f32_e32 v61, v62, v61
	v_mul_f32_e32 v62, v183, v4
	v_add_f32_e32 v61, v62, v61
	s_waitcnt lgkmcnt(5)
	s_waitcnt lgkmcnt(4)
	v_mul_f32_e32 v62, v184, v7
	v_add_f32_e32 v61, v62, v61
	v_mul_f32_e32 v62, v188, v6
	v_add_f32_e32 v61, v62, v61
	v_mul_f32_e32 v62, v185, v9
	v_add_f32_e32 v61, v62, v61
	v_mul_f32_e32 v62, v189, v8
	v_add_f32_e32 v61, v62, v61
	v_mul_f32_e32 v62, v186, v11
	v_add_f32_e32 v61, v62, v61
	v_mul_f32_e32 v62, v190, v10
	v_add_f32_e32 v61, v62, v61
	v_mul_f32_e32 v62, v187, v13
	v_add_f32_e32 v61, v62, v61
	v_mul_f32_e32 v62, v191, v12
	v_add_f32_e32 v61, v62, v61
	v_mov_b32_e32 v203, v61
	ds_read_b128 v[176:179], v36 offset:2944
	ds_read_b128 v[180:183], v36 offset:2960
	ds_read_b128 v[184:187], v36 offset:3008
	ds_read_b128 v[188:191], v36 offset:3024
	s_cmp_eq_u32 s37, 11
	s_cbranch_scc1 .Lgate_b
; __device__ __forceinline__ float bf2f(unsigned v) { return __uint_as_float(v << 16); }
; __device__ void attn_item(const Params& p, char* lds, int bh, int qi) {
;     ...
;     for (int j = 0; j < qi; ++j) {
;       float g = 0.f;
; #pragma unroll
;       for (int ks = 0; ks < 4; ++ks) {
;         const f32x4 ka = *(const f32x4*)(km + j * 64 + ks * 16 + 8 * h);
;         const f32x4 kb = *(const f32x4*)(km + j * 64 + ks * 16 + 8 * h + 4);
; #pragma unroll
;         for (int e = 0; e < 4; ++e) {
;           g += bf2f((unsigned)(u16)qf[ks][e]) * ka[e];
;           g += bf2f((unsigned)(u16)qf[ks][4 + e]) * kb[e];
;         }
;       }
	s_waitcnt lgkmcnt(7)
	s_waitcnt lgkmcnt(6)
	v_fma_f32 v61, v42, v15, 0
	v_fmac_f32_e32 v61, v46, v16
	v_fmac_f32_e32 v61, v43, v17
	v_fmac_f32_e32 v61, v47, v18
	v_fmac_f32_e32 v61, v44, v19
	v_fmac_f32_e32 v61, v48, v20
	v_fmac_f32_e32 v61, v45, v21
	v_fmac_f32_e32 v61, v49, v22
	s_waitcnt lgkmcnt(5)
	s_waitcnt lgkmcnt(4)
	v_fmac_f32_e32 v61, v50, v23
	v_fmac_f32_e32 v61, v54, v24
	v_fmac_f32_e32 v61, v51, v25
	v_fmac_f32_e32 v61, v55, v26
	v_fmac_f32_e32 v61, v52, v27
	v_fmac_f32_e32 v61, v56, v28
	v_fmac_f32_e32 v61, v53, v29
	v_fmac_f32_e32 v61, v57, v30
	ds_read_b128 v[42:45], v36 offset:3072
	ds_read_b128 v[46:49], v36 offset:3088
	ds_read_b128 v[50:53], v36 offset:3136
	ds_read_b128 v[54:57], v36 offset:3152
	s_waitcnt lgkmcnt(7)
	s_waitcnt lgkmcnt(6)
	v_fmac_f32_e32 v61, v176, v31
	v_fmac_f32_e32 v61, v180, v32
	v_fmac_f32_e32 v61, v177, v33
	v_fmac_f32_e32 v61, v181, v35
	v_mul_f32_e32 v62, v178, v3
	v_add_f32_e32 v61, v62, v61
	v_mul_f32_e32 v62, v182, v2
	v_add_f32_e32 v61, v62, v61
	v_mul_f32_e32 v62, v179, v5
	v_add_f32_e32 v61, v62, v61
	v_mul_f32_e32 v62, v183, v4
	v_add_f32_e32 v61, v62, v61
	s_waitcnt lgkmcnt(5)
	s_waitcnt lgkmcnt(4)
	v_mul_f32_e32 v62, v184, v7
	v_add_f32_e32 v61, v62, v61
	v_mul_f32_e32 v62, v188, v6
	v_add_f32_e32 v61, v62, v61
	v_mul_f32_e32 v62, v185, v9
	v_add_f32_e32 v61, v62, v61
	v_mul_f32_e32 v62, v189, v8
	v_add_f32_e32 v61, v62, v61
	v_mul_f32_e32 v62, v186, v11
	v_add_f32_e32 v61, v62, v61
	v_mul_f32_e32 v62, v190, v10
	v_add_f32_e32 v61, v62, v61
	v_mul_f32_e32 v62, v187, v13
	v_add_f32_e32 v61, v62, v61
	v_mul_f32_e32 v62, v191, v12
	v_add_f32_e32 v61, v62, v61
	v_mov_b32_e32 v204, v61
	ds_read_b128 v[176:179], v36 offset:3200
	ds_read_b128 v[180:183], v36 offset:3216
	ds_read_b128 v[184:187], v36 offset:3264
	ds_read_b128 v[188:191], v36 offset:3280
	s_cmp_eq_u32 s37, 12
	s_cbranch_scc1 .Lgate_b
	s_waitcnt lgkmcnt(7)
	s_waitcnt lgkmcnt(6)
	v_fma_f32 v61, v42, v15, 0
	v_fmac_f32_e32 v61, v46, v16
	v_fmac_f32_e32 v61, v43, v17
	v_fmac_f32_e32 v61, v47, v18
	v_fmac_f32_e32 v61, v44, v19
	v_fmac_f32_e32 v61, v48, v20
	v_fmac_f32_e32 v61, v45, v21
	v_fmac_f32_e32 v61, v49, v22
	s_waitcnt lgkmcnt(5)
	s_waitcnt lgkmcnt(4)
	v_fmac_f32_e32 v61, v50, v23
	v_fmac_f32_e32 v61, v54, v24
	v_fmac_f32_e32 v61, v51, v25
	v_fmac_f32_e32 v61, v55, v26
	v_fmac_f32_e32 v61, v52, v27
	v_fmac_f32_e32 v61, v56, v28
	v_fmac_f32_e32 v61, v53, v29
	v_fmac_f32_e32 v61, v57, v30
	ds_read_b128 v[42:45], v36 offset:3328
	ds_read_b128 v[46:49], v36 offset:3344
	ds_read_b128 v[50:53], v36 offset:3392
	ds_read_b128 v[54:57], v36 offset:3408
	s_waitcnt lgkmcnt(7)
	s_waitcnt lgkmcnt(6)
	v_fmac_f32_e32 v61, v176, v31
	v_fmac_f32_e32 v61, v180, v32
	v_fmac_f32_e32 v61, v177, v33
	v_fmac_f32_e32 v61, v181, v35
	v_mul_f32_e32 v62, v178, v3
	v_add_f32_e32 v61, v62, v61
	v_mul_f32_e32 v62, v182, v2
	v_add_f32_e32 v61, v62, v61
	v_mul_f32_e32 v62, v179, v5
	v_add_f32_e32 v61, v62, v61
	v_mul_f32_e32 v62, v183, v4
	v_add_f32_e32 v61, v62, v61
	s_waitcnt lgkmcnt(5)
	s_waitcnt lgkmcnt(4)
	v_mul_f32_e32 v62, v184, v7
	v_add_f32_e32 v61, v62, v61
	v_mul_f32_e32 v62, v188, v6
	v_add_f32_e32 v61, v62, v61
	v_mul_f32_e32 v62, v185, v9
	v_add_f32_e32 v61, v62, v61
	v_mul_f32_e32 v62, v189, v8
	v_add_f32_e32 v61, v62, v61
	v_mul_f32_e32 v62, v186, v11
	v_add_f32_e32 v61, v62, v61
	v_mul_f32_e32 v62, v190, v10
	v_add_f32_e32 v61, v62, v61
	v_mul_f32_e32 v62, v187, v13
	v_add_f32_e32 v61, v62, v61
	v_mul_f32_e32 v62, v191, v12
	v_add_f32_e32 v61, v62, v61
	v_mov_b32_e32 v205, v61
	ds_read_b128 v[176:179], v36 offset:3456
	ds_read_b128 v[180:183], v36 offset:3472
	ds_read_b128 v[184:187], v36 offset:3520
	ds_read_b128 v[188:191], v36 offset:3536
	s_cmp_eq_u32 s37, 13
	s_cbranch_scc1 .Lgate_b
	s_waitcnt lgkmcnt(7)
	s_waitcnt lgkmcnt(6)
	v_fma_f32 v61, v42, v15, 0
	v_fmac_f32_e32 v61, v46, v16
	v_fmac_f32_e32 v61, v43, v17
	v_fmac_f32_e32 v61, v47, v18
	v_fmac_f32_e32 v61, v44, v19
	v_fmac_f32_e32 v61, v48, v20
	v_fmac_f32_e32 v61, v45, v21
	v_fmac_f32_e32 v61, v49, v22
	s_waitcnt lgkmcnt(5)
	s_waitcnt lgkmcnt(4)
	v_fmac_f32_e32 v61, v50, v23
	v_fmac_f32_e32 v61, v54, v24
	v_fmac_f32_e32 v61, v51, v25
	v_fmac_f32_e32 v61, v55, v26
	v_fmac_f32_e32 v61, v52, v27
	v_fmac_f32_e32 v61, v56, v28
	v_fmac_f32_e32 v61, v53, v29
	v_fmac_f32_e32 v61, v57, v30
	ds_read_b128 v[42:45], v36 offset:3584
	ds_read_b128 v[46:49], v36 offset:3600
	ds_read_b128 v[50:53], v36 offset:3648
	ds_read_b128 v[54:57], v36 offset:3664
	s_waitcnt lgkmcnt(7)
	s_waitcnt lgkmcnt(6)
	v_fmac_f32_e32 v61, v176, v31
	v_fmac_f32_e32 v61, v180, v32
	v_fmac_f32_e32 v61, v177, v33
	v_fmac_f32_e32 v61, v181, v35
	v_mul_f32_e32 v62, v178, v3
	v_add_f32_e32 v61, v62, v61
	v_mul_f32_e32 v62, v182, v2
	v_add_f32_e32 v61, v62, v61
	v_mul_f32_e32 v62, v179, v5
	v_add_f32_e32 v61, v62, v61
	v_mul_f32_e32 v62, v183, v4
	v_add_f32_e32 v61, v62, v61
	s_waitcnt lgkmcnt(5)
	s_waitcnt lgkmcnt(4)
	v_mul_f32_e32 v62, v184, v7
	v_add_f32_e32 v61, v62, v61
	v_mul_f32_e32 v62, v188, v6
	v_add_f32_e32 v61, v62, v61
	v_mul_f32_e32 v62, v185, v9
	v_add_f32_e32 v61, v62, v61
	v_mul_f32_e32 v62, v189, v8
	v_add_f32_e32 v61, v62, v61
	v_mul_f32_e32 v62, v186, v11
	v_add_f32_e32 v61, v62, v61
	v_mul_f32_e32 v62, v190, v10
	v_add_f32_e32 v61, v62, v61
	v_mul_f32_e32 v62, v187, v13
	v_add_f32_e32 v61, v62, v61
	v_mul_f32_e32 v62, v191, v12
	v_add_f32_e32 v61, v62, v61
	v_mov_b32_e32 v206, v61
	ds_read_b128 v[176:179], v36 offset:3712
	ds_read_b128 v[180:183], v36 offset:3728
	ds_read_b128 v[184:187], v36 offset:3776
	ds_read_b128 v[188:191], v36 offset:3792
	s_cmp_eq_u32 s37, 14
	s_cbranch_scc1 .Lgate_b
; __device__ __forceinline__ float bf2f(unsigned v) { return __uint_as_float(v << 16); }
; __device__ void attn_item(const Params& p, char* lds, int bh, int qi) {
;     ...
;     for (int j = 0; j < qi; ++j) {
;       float g = 0.f;
; #pragma unroll
;       for (int ks = 0; ks < 4; ++ks) {
;         const f32x4 ka = *(const f32x4*)(km + j * 64 + ks * 16 + 8 * h);
;         const f32x4 kb = *(const f32x4*)(km + j * 64 + ks * 16 + 8 * h + 4);
; #pragma unroll
;         for (int e = 0; e < 4; ++e) {
;           g += bf2f((unsigned)(u16)qf[ks][e]) * ka[e];
;           g += bf2f((unsigned)(u16)qf[ks][4 + e]) * kb[e];
;         }
;       }
;       g += __shfl_xor(g, 32);
;       if (g > v0) { v2 = v1; i2 = i1; v1 = v0; i1 = i0; v0 = g; i0 = j; }
;       else if (g > v1) { v2 = v1; i2 = i1; v1 = g; i1 = j; }
;       else if (g > v2) { v2 = g; i2 = j; }
;     }
;     selmask = (1u << i0) | (1u << i1) | (1u << i2);
	s_waitcnt lgkmcnt(7)
	s_waitcnt lgkmcnt(6)
	v_fma_f32 v61, v42, v15, 0
	v_fmac_f32_e32 v61, v46, v16
	v_fmac_f32_e32 v61, v43, v17
	v_fmac_f32_e32 v61, v47, v18
	v_fmac_f32_e32 v61, v44, v19
	v_fmac_f32_e32 v61, v48, v20
	v_fmac_f32_e32 v61, v45, v21
	v_fmac_f32_e32 v61, v49, v22
	s_waitcnt lgkmcnt(5)
	s_waitcnt lgkmcnt(4)
	v_fmac_f32_e32 v61, v50, v23
	v_fmac_f32_e32 v61, v54, v24
	v_fmac_f32_e32 v61, v51, v25
	v_fmac_f32_e32 v61, v55, v26
	v_fmac_f32_e32 v61, v52, v27
	v_fmac_f32_e32 v61, v56, v28
	v_fmac_f32_e32 v61, v53, v29
	v_fmac_f32_e32 v61, v57, v30
	s_waitcnt lgkmcnt(3)
	s_waitcnt lgkmcnt(2)
	v_fmac_f32_e32 v61, v176, v31
	v_fmac_f32_e32 v61, v180, v32
	v_fmac_f32_e32 v61, v177, v33
	v_fmac_f32_e32 v61, v181, v35
	v_mul_f32_e32 v62, v178, v3
	v_add_f32_e32 v61, v62, v61
	v_mul_f32_e32 v62, v182, v2
	v_add_f32_e32 v61, v62, v61
	v_mul_f32_e32 v62, v179, v5
	v_add_f32_e32 v61, v62, v61
	v_mul_f32_e32 v62, v183, v4
	v_add_f32_e32 v61, v62, v61
	s_waitcnt lgkmcnt(1)
	s_waitcnt lgkmcnt(0)
	v_mul_f32_e32 v62, v184, v7
	v_add_f32_e32 v61, v62, v61
	v_mul_f32_e32 v62, v188, v6
	v_add_f32_e32 v61, v62, v61
	v_mul_f32_e32 v62, v185, v9
	v_add_f32_e32 v61, v62, v61
	v_mul_f32_e32 v62, v189, v8
	v_add_f32_e32 v61, v62, v61
	v_mul_f32_e32 v62, v186, v11
	v_add_f32_e32 v61, v62, v61
	v_mul_f32_e32 v62, v190, v10
	v_add_f32_e32 v61, v62, v61
	v_mul_f32_e32 v62, v187, v13
	v_add_f32_e32 v61, v62, v61
	v_mul_f32_e32 v62, v191, v12
	v_add_f32_e32 v61, v62, v61
	v_mov_b32_e32 v207, v61
.Lgate_b:
	ds_bpermute_b32 v42, v14, v193
	ds_bpermute_b32 v43, v14, v194
	ds_bpermute_b32 v44, v14, v195
	ds_bpermute_b32 v45, v14, v196
	s_cmp_eq_u32 s37, 4
	s_cbranch_scc1 .Lgate_c
	ds_bpermute_b32 v46, v14, v197
	s_cmp_eq_u32 s37, 5
	s_cbranch_scc1 .Lgate_c
	ds_bpermute_b32 v47, v14, v198
	s_cmp_eq_u32 s37, 6
	s_cbranch_scc1 .Lgate_c
	ds_bpermute_b32 v48, v14, v199
	s_cmp_eq_u32 s37, 7
	s_cbranch_scc1 .Lgate_c
	ds_bpermute_b32 v49, v14, v200
	s_cmp_eq_u32 s37, 8
	s_cbranch_scc1 .Lgate_c
	ds_bpermute_b32 v50, v14, v201
	s_cmp_eq_u32 s37, 9
	s_cbranch_scc1 .Lgate_c
	ds_bpermute_b32 v51, v14, v202
	s_cmp_eq_u32 s37, 10
	s_cbranch_scc1 .Lgate_c
	ds_bpermute_b32 v52, v14, v203
	s_cmp_eq_u32 s37, 11
	s_cbranch_scc1 .Lgate_c
	ds_bpermute_b32 v53, v14, v204
	s_cmp_eq_u32 s37, 12
	s_cbranch_scc1 .Lgate_c
	ds_bpermute_b32 v54, v14, v205
	s_cmp_eq_u32 s37, 13
	s_cbranch_scc1 .Lgate_c
	ds_bpermute_b32 v55, v14, v206
	s_cmp_eq_u32 s37, 14
	s_cbranch_scc1 .Lgate_c
	ds_bpermute_b32 v56, v14, v207
.Lgate_c:
	v_mov_b32_e32 v37, 0xff800000
	v_mov_b32_e32 v38, 0xff800000
	v_mov_b32_e32 v41, 0xff800000
	v_mov_b32_e32 v34, 0
	v_mov_b32_e32 v39, 0
	v_mov_b32_e32 v40, 0
	s_waitcnt lgkmcnt(0)
	v_add_f32_e32 v58, v193, v42
	v_cmp_gt_f32_e64 s[14:15], v58, v37
	v_cmp_gt_f32_e64 s[18:19], v58, v38
	v_cmp_gt_f32_e64 s[20:21], v58, v41
	s_nop 1
	v_cndmask_b32_e64 v59, v41, v58, s[20:21]
	v_cndmask_b32_e64 v60, v40, 0, s[20:21]
	v_cndmask_b32_e64 v41, v59, v38, s[18:19]
	v_cndmask_b32_e64 v40, v60, v39, s[18:19]
	v_cndmask_b32_e64 v59, v38, v58, s[18:19]
	v_cndmask_b32_e64 v60, v39, 0, s[18:19]
	v_cndmask_b32_e64 v38, v59, v37, s[14:15]
	v_cndmask_b32_e64 v39, v60, v34, s[14:15]
	v_cndmask_b32_e64 v37, v37, v58, s[14:15]
	v_cndmask_b32_e64 v34, v34, 0, s[14:15]
	v_add_f32_e32 v58, v194, v43
	v_cmp_gt_f32_e64 s[14:15], v58, v37
	v_cmp_gt_f32_e64 s[18:19], v58, v38
	v_cmp_gt_f32_e64 s[20:21], v58, v41
	s_nop 1
	v_cndmask_b32_e64 v59, v41, v58, s[20:21]
	v_cndmask_b32_e64 v60, v40, 1, s[20:21]
	v_cndmask_b32_e64 v41, v59, v38, s[18:19]
	v_cndmask_b32_e64 v40, v60, v39, s[18:19]
	v_cndmask_b32_e64 v59, v38, v58, s[18:19]
	v_cndmask_b32_e64 v60, v39, 1, s[18:19]
	v_cndmask_b32_e64 v38, v59, v37, s[14:15]
	v_cndmask_b32_e64 v39, v60, v34, s[14:15]
	v_cndmask_b32_e64 v37, v37, v58, s[14:15]
	v_cndmask_b32_e64 v34, v34, 1, s[14:15]
	v_add_f32_e32 v58, v195, v44
	v_cmp_gt_f32_e64 s[14:15], v58, v37
	v_cmp_gt_f32_e64 s[18:19], v58, v38
	v_cmp_gt_f32_e64 s[20:21], v58, v41
	s_nop 1
	v_cndmask_b32_e64 v59, v41, v58, s[20:21]
	v_cndmask_b32_e64 v60, v40, 2, s[20:21]
	v_cndmask_b32_e64 v41, v59, v38, s[18:19]
	v_cndmask_b32_e64 v40, v60, v39, s[18:19]
	v_cndmask_b32_e64 v59, v38, v58, s[18:19]
	v_cndmask_b32_e64 v60, v39, 2, s[18:19]
	v_cndmask_b32_e64 v38, v59, v37, s[14:15]
	v_cndmask_b32_e64 v39, v60, v34, s[14:15]
	v_cndmask_b32_e64 v37, v37, v58, s[14:15]
	v_cndmask_b32_e64 v34, v34, 2, s[14:15]
	v_add_f32_e32 v58, v196, v45
	v_cmp_gt_f32_e64 s[14:15], v58, v37
	v_cmp_gt_f32_e64 s[18:19], v58, v38
	v_cmp_gt_f32_e64 s[20:21], v58, v41
	s_nop 1
	v_cndmask_b32_e64 v59, v41, v58, s[20:21]
	v_cndmask_b32_e64 v60, v40, 3, s[20:21]
	v_cndmask_b32_e64 v41, v59, v38, s[18:19]
	v_cndmask_b32_e64 v40, v60, v39, s[18:19]
	v_cndmask_b32_e64 v59, v38, v58, s[18:19]
	v_cndmask_b32_e64 v60, v39, 3, s[18:19]
	v_cndmask_b32_e64 v38, v59, v37, s[14:15]
	v_cndmask_b32_e64 v39, v60, v34, s[14:15]
	v_cndmask_b32_e64 v37, v37, v58, s[14:15]
	v_cndmask_b32_e64 v34, v34, 3, s[14:15]
	s_cmp_eq_u32 s37, 4
	s_cbranch_scc1 .Lgate_d
	v_add_f32_e32 v58, v197, v46
	v_cmp_gt_f32_e64 s[14:15], v58, v37
	v_cmp_gt_f32_e64 s[18:19], v58, v38
	v_cmp_gt_f32_e64 s[20:21], v58, v41
	s_nop 1
	v_cndmask_b32_e64 v59, v41, v58, s[20:21]
	v_cndmask_b32_e64 v60, v40, 4, s[20:21]
	v_cndmask_b32_e64 v41, v59, v38, s[18:19]
	v_cndmask_b32_e64 v40, v60, v39, s[18:19]
	v_cndmask_b32_e64 v59, v38, v58, s[18:19]
	v_cndmask_b32_e64 v60, v39, 4, s[18:19]
	v_cndmask_b32_e64 v38, v59, v37, s[14:15]
	v_cndmask_b32_e64 v39, v60, v34, s[14:15]
	v_cndmask_b32_e64 v37, v37, v58, s[14:15]
	v_cndmask_b32_e64 v34, v34, 4, s[14:15]
	s_cmp_eq_u32 s37, 5
	s_cbranch_scc1 .Lgate_d
; __device__ void attn_item(const Params& p, char* lds, int bh, int qi) {
;     ...
;       g += __shfl_xor(g, 32);
;       if (g > v0) { v2 = v1; i2 = i1; v1 = v0; i1 = i0; v0 = g; i0 = j; }
;       else if (g > v1) { v2 = v1; i2 = i1; v1 = g; i1 = j; }
;       else if (g > v2) { v2 = g; i2 = j; }
;     }
;     selmask = (1u << i0) | (1u << i1) | (1u << i2);
	v_add_f32_e32 v58, v198, v47
	v_cmp_gt_f32_e64 s[14:15], v58, v37
	v_cmp_gt_f32_e64 s[18:19], v58, v38
	v_cmp_gt_f32_e64 s[20:21], v58, v41
	s_nop 1
	v_cndmask_b32_e64 v59, v41, v58, s[20:21]
	v_cndmask_b32_e64 v60, v40, 5, s[20:21]
	v_cndmask_b32_e64 v41, v59, v38, s[18:19]
	v_cndmask_b32_e64 v40, v60, v39, s[18:19]
	v_cndmask_b32_e64 v59, v38, v58, s[18:19]
	v_cndmask_b32_e64 v60, v39, 5, s[18:19]
	v_cndmask_b32_e64 v38, v59, v37, s[14:15]
	v_cndmask_b32_e64 v39, v60, v34, s[14:15]
	v_cndmask_b32_e64 v37, v37, v58, s[14:15]
	v_cndmask_b32_e64 v34, v34, 5, s[14:15]
	s_cmp_eq_u32 s37, 6
	s_cbranch_scc1 .Lgate_d
	v_add_f32_e32 v58, v199, v48
	v_cmp_gt_f32_e64 s[14:15], v58, v37
	v_cmp_gt_f32_e64 s[18:19], v58, v38
	v_cmp_gt_f32_e64 s[20:21], v58, v41
	s_nop 1
	v_cndmask_b32_e64 v59, v41, v58, s[20:21]
	v_cndmask_b32_e64 v60, v40, 6, s[20:21]
	v_cndmask_b32_e64 v41, v59, v38, s[18:19]
	v_cndmask_b32_e64 v40, v60, v39, s[18:19]
	v_cndmask_b32_e64 v59, v38, v58, s[18:19]
	v_cndmask_b32_e64 v60, v39, 6, s[18:19]
	v_cndmask_b32_e64 v38, v59, v37, s[14:15]
	v_cndmask_b32_e64 v39, v60, v34, s[14:15]
	v_cndmask_b32_e64 v37, v37, v58, s[14:15]
	v_cndmask_b32_e64 v34, v34, 6, s[14:15]
	s_cmp_eq_u32 s37, 7
	s_cbranch_scc1 .Lgate_d
	v_add_f32_e32 v58, v200, v49
	v_cmp_gt_f32_e64 s[14:15], v58, v37
	v_cmp_gt_f32_e64 s[18:19], v58, v38
	v_cmp_gt_f32_e64 s[20:21], v58, v41
	s_nop 1
	v_cndmask_b32_e64 v59, v41, v58, s[20:21]
	v_cndmask_b32_e64 v60, v40, 7, s[20:21]
	v_cndmask_b32_e64 v41, v59, v38, s[18:19]
	v_cndmask_b32_e64 v40, v60, v39, s[18:19]
	v_cndmask_b32_e64 v59, v38, v58, s[18:19]
	v_cndmask_b32_e64 v60, v39, 7, s[18:19]
	v_cndmask_b32_e64 v38, v59, v37, s[14:15]
	v_cndmask_b32_e64 v39, v60, v34, s[14:15]
	v_cndmask_b32_e64 v37, v37, v58, s[14:15]
	v_cndmask_b32_e64 v34, v34, 7, s[14:15]
	s_cmp_eq_u32 s37, 8
	s_cbranch_scc1 .Lgate_d
	v_add_f32_e32 v58, v201, v50
	v_cmp_gt_f32_e64 s[14:15], v58, v37
	v_cmp_gt_f32_e64 s[18:19], v58, v38
	v_cmp_gt_f32_e64 s[20:21], v58, v41
	s_nop 1
	v_cndmask_b32_e64 v59, v41, v58, s[20:21]
	v_cndmask_b32_e64 v60, v40, 8, s[20:21]
	v_cndmask_b32_e64 v41, v59, v38, s[18:19]
	v_cndmask_b32_e64 v40, v60, v39, s[18:19]
	v_cndmask_b32_e64 v59, v38, v58, s[18:19]
	v_cndmask_b32_e64 v60, v39, 8, s[18:19]
	v_cndmask_b32_e64 v38, v59, v37, s[14:15]
	v_cndmask_b32_e64 v39, v60, v34, s[14:15]
	v_cndmask_b32_e64 v37, v37, v58, s[14:15]
	v_cndmask_b32_e64 v34, v34, 8, s[14:15]
	s_cmp_eq_u32 s37, 9
	s_cbranch_scc1 .Lgate_d
	v_add_f32_e32 v58, v202, v51
	v_cmp_gt_f32_e64 s[14:15], v58, v37
	v_cmp_gt_f32_e64 s[18:19], v58, v38
	v_cmp_gt_f32_e64 s[20:21], v58, v41
	s_nop 1
	v_cndmask_b32_e64 v59, v41, v58, s[20:21]
	v_cndmask_b32_e64 v60, v40, 9, s[20:21]
	v_cndmask_b32_e64 v41, v59, v38, s[18:19]
	v_cndmask_b32_e64 v40, v60, v39, s[18:19]
	v_cndmask_b32_e64 v59, v38, v58, s[18:19]
	v_cndmask_b32_e64 v60, v39, 9, s[18:19]
	v_cndmask_b32_e64 v38, v59, v37, s[14:15]
	v_cndmask_b32_e64 v39, v60, v34, s[14:15]
	v_cndmask_b32_e64 v37, v37, v58, s[14:15]
	v_cndmask_b32_e64 v34, v34, 9, s[14:15]
	s_cmp_eq_u32 s37, 10
	s_cbranch_scc1 .Lgate_d
	v_add_f32_e32 v58, v203, v52
	v_cmp_gt_f32_e64 s[14:15], v58, v37
	v_cmp_gt_f32_e64 s[18:19], v58, v38
	v_cmp_gt_f32_e64 s[20:21], v58, v41
	s_nop 1
	v_cndmask_b32_e64 v59, v41, v58, s[20:21]
	v_cndmask_b32_e64 v60, v40, 10, s[20:21]
	v_cndmask_b32_e64 v41, v59, v38, s[18:19]
	v_cndmask_b32_e64 v40, v60, v39, s[18:19]
	v_cndmask_b32_e64 v59, v38, v58, s[18:19]
	v_cndmask_b32_e64 v60, v39, 10, s[18:19]
	v_cndmask_b32_e64 v38, v59, v37, s[14:15]
	v_cndmask_b32_e64 v39, v60, v34, s[14:15]
	v_cndmask_b32_e64 v37, v37, v58, s[14:15]
	v_cndmask_b32_e64 v34, v34, 10, s[14:15]
	s_cmp_eq_u32 s37, 11
	s_cbranch_scc1 .Lgate_d
	v_add_f32_e32 v58, v204, v53
	v_cmp_gt_f32_e64 s[14:15], v58, v37
	v_cmp_gt_f32_e64 s[18:19], v58, v38
	v_cmp_gt_f32_e64 s[20:21], v58, v41
	s_nop 1
	v_cndmask_b32_e64 v59, v41, v58, s[20:21]
	v_cndmask_b32_e64 v60, v40, 11, s[20:21]
	v_cndmask_b32_e64 v41, v59, v38, s[18:19]
	v_cndmask_b32_e64 v40, v60, v39, s[18:19]
	v_cndmask_b32_e64 v59, v38, v58, s[18:19]
	v_cndmask_b32_e64 v60, v39, 11, s[18:19]
	v_cndmask_b32_e64 v38, v59, v37, s[14:15]
	v_cndmask_b32_e64 v39, v60, v34, s[14:15]
	v_cndmask_b32_e64 v37, v37, v58, s[14:15]
	v_cndmask_b32_e64 v34, v34, 11, s[14:15]
	s_cmp_eq_u32 s37, 12
	s_cbranch_scc1 .Lgate_d
	v_add_f32_e32 v58, v205, v54
	v_cmp_gt_f32_e64 s[14:15], v58, v37
	v_cmp_gt_f32_e64 s[18:19], v58, v38
	v_cmp_gt_f32_e64 s[20:21], v58, v41
	s_nop 1
	v_cndmask_b32_e64 v59, v41, v58, s[20:21]
	v_cndmask_b32_e64 v60, v40, 12, s[20:21]
	v_cndmask_b32_e64 v41, v59, v38, s[18:19]
	v_cndmask_b32_e64 v40, v60, v39, s[18:19]
	v_cndmask_b32_e64 v59, v38, v58, s[18:19]
	v_cndmask_b32_e64 v60, v39, 12, s[18:19]
	v_cndmask_b32_e64 v38, v59, v37, s[14:15]
	v_cndmask_b32_e64 v39, v60, v34, s[14:15]
	v_cndmask_b32_e64 v37, v37, v58, s[14:15]
	v_cndmask_b32_e64 v34, v34, 12, s[14:15]
	s_cmp_eq_u32 s37, 13
	s_cbranch_scc1 .Lgate_d
	v_add_f32_e32 v58, v206, v55
	v_cmp_gt_f32_e64 s[14:15], v58, v37
	v_cmp_gt_f32_e64 s[18:19], v58, v38
	v_cmp_gt_f32_e64 s[20:21], v58, v41
	s_nop 1
	v_cndmask_b32_e64 v59, v41, v58, s[20:21]
	v_cndmask_b32_e64 v60, v40, 13, s[20:21]
	v_cndmask_b32_e64 v41, v59, v38, s[18:19]
	v_cndmask_b32_e64 v40, v60, v39, s[18:19]
	v_cndmask_b32_e64 v59, v38, v58, s[18:19]
	v_cndmask_b32_e64 v60, v39, 13, s[18:19]
	v_cndmask_b32_e64 v38, v59, v37, s[14:15]
	v_cndmask_b32_e64 v39, v60, v34, s[14:15]
	v_cndmask_b32_e64 v37, v37, v58, s[14:15]
	v_cndmask_b32_e64 v34, v34, 13, s[14:15]
	s_cmp_eq_u32 s37, 14
	s_cbranch_scc1 .Lgate_d
	v_add_f32_e32 v58, v207, v56
	v_cmp_gt_f32_e64 s[14:15], v58, v37
	v_cmp_gt_f32_e64 s[18:19], v58, v38
	v_cmp_gt_f32_e64 s[20:21], v58, v41
	s_nop 1
	v_cndmask_b32_e64 v59, v41, v58, s[20:21]
	v_cndmask_b32_e64 v60, v40, 14, s[20:21]
	v_cndmask_b32_e64 v41, v59, v38, s[18:19]
	v_cndmask_b32_e64 v40, v60, v39, s[18:19]
	v_cndmask_b32_e64 v59, v38, v58, s[18:19]
	v_cndmask_b32_e64 v60, v39, 14, s[18:19]
	v_cndmask_b32_e64 v38, v59, v37, s[14:15]
	v_cndmask_b32_e64 v39, v60, v34, s[14:15]
	v_cndmask_b32_e64 v37, v37, v58, s[14:15]
	v_cndmask_b32_e64 v34, v34, 14, s[14:15]
.Lgate_d:
	v_lshlrev_b32_e64 v2, v34, 1
	v_lshlrev_b32_e64 v3, v39, 1
	v_lshlrev_b32_e64 v4, v40, 1
	v_or3_b32 v105, v3, v4, v2
	s_mov_b64 s[14:15], 0
